# differential-attention bias-table tiles: 16 LDS address adds folded into ds_read2_b32 offset immediates (on top of A-loop mov removal)
# speedup vs baseline: 1.0143x; 1.0012x over previous
.LBB0_470:
	s_and_b32 s29, s55, 0x1fc000
	s_cmpk_lt_u32 s57, 0x7f
	s_cselect_b32 s29, s29, 0x1fc000
	s_add_u32 s52, s48, s29
	s_addc_u32 s53, s49, 0
	s_and_b32 s29, s57, 0x7f
	s_mul_i32 s36, s29, 0x230000
	global_load_dwordx4 v[112:115], v201, s[52:53]
	global_load_dwordx4 v[116:119], v208, s[52:53]
	s_add_u32 s52, s50, s36
	s_addc_u32 s53, s51, 0
	global_load_dwordx4 v[120:123], v209, s[52:53]
	global_load_dwordx4 v[124:127], v210, s[52:53]
	s_lshl_b32 s29, s29, 6
	s_sub_i32 s58, s29, s56
	s_add_i32 s36, s58, 0xfffffdb2
	s_cmp_gt_u32 s36, 0xfffffb44
	s_mov_b64 s[52:53], -1
	s_cbranch_scc0 .LBB0_472
	v_sub_u32_e32 v80, s29, v162
	v_lshl_add_u32 v163, v80, 2, v203
	v_add_u32_e32 v163, 0xffc, v163
	ds_read2_b32 v[96:97], v163 offset1:1
	ds_read2_b32 v[80:81], v163 offset0:32 offset1:33
	ds_read2_b32 v[98:99], v163 offset0:2 offset1:3
	ds_read2_b32 v[82:83], v163 offset0:34 offset1:35
	ds_read2_b32 v[100:101], v163 offset0:8 offset1:9
	ds_read2_b32 v[84:85], v163 offset0:40 offset1:41
	ds_read2_b32 v[102:103], v163 offset0:10 offset1:11
	ds_read2_b32 v[86:87], v163 offset0:42 offset1:43
	ds_read2_b32 v[104:105], v163 offset0:16 offset1:17
	ds_read2_b32 v[88:89], v163 offset0:48 offset1:49
	ds_read2_b32 v[106:107], v163 offset0:18 offset1:19
	ds_read2_b32 v[90:91], v163 offset0:50 offset1:51
	ds_read2_b32 v[108:109], v163 offset0:24 offset1:25
	ds_read2_b32 v[92:93], v163 offset0:56 offset1:57
	ds_read2_b32 v[110:111], v163 offset0:26 offset1:27
	ds_read2_b32 v[94:95], v163 offset0:58 offset1:59
	s_mov_b64 s[52:53], 0
